# attention V-fragment LDS reads: split 16 ds_read2_b64 into ds_read_b64 pairs (full-rate LDS path)
# speedup vs baseline: 1.0111x; 1.0111x over previous
; __device__ __forceinline__ unsigned pk2(float lo, float hi) { return pg8::cvtpk(lo, hi); }
; #define MFMA16(a, b, c) __builtin_amdgcn_mfma_f32_16x16x32_bf16((a), (b), (c), 0, 0, 0)
; #define AT_SB __builtin_amdgcn_sched_barrier(0)
; #define AT_VLD(dst, g_) do { _Pragma("unroll") for (int i_ = 0; i_ < 4; ++i_) { const LAS unsigned char* vp = Vl + (16 * (4 * ((g_) & 1) + i_) + fr) * 144 + (32 * ((g_) >> 1) + 4 * fq) * 2; \
;             const u32x2 lo = *(const LAS u32x2*)vp, hi = *(const LAS u32x2*)(vp + 32); u32x4 w; w.x = lo.x; w.y = lo.y; w.z = hi.x; w.w = hi.y; dst[i_] = __builtin_bit_cast(bf16x8, w); } } while (0)
; __device__ __forceinline__ void attn_unit(const Params& P, LAS unsigned char* lds, int bh, int qb) {
;     ...
;             bf16x8 pf[2][2];
; #pragma unroll
;             for (int qk = 0; qk < 2; ++qk) {
; #pragma unroll
;                 for (int kvb = 0; kvb < 4; ++kvb)
; #pragma unroll
;                     for (int e = 0; e < 4; ++e) s[kvb][qk][e] = __builtin_amdgcn_exp2f(s[kvb][qk][e]);
; #pragma unroll
;                 for (int s2 = 0; s2 < 2; ++s2) { u32x4 w; w.x = pk2(s[2 * s2][qk][0], s[2 * s2][qk][1]); w.y = pk2(s[2 * s2][qk][2], s[2 * s2][qk][3]);
;                     w.z = pk2(s[2 * s2 + 1][qk][0], s[2 * s2 + 1][qk][1]); w.w = pk2(s[2 * s2 + 1][qk][2], s[2 * s2 + 1][qk][3]); pf[s2][qk] = __builtin_bit_cast(bf16x8, w); } }
;             AT_SB;
; #pragma unroll
;             for (int g = 0; g < 4; ++g) {
;                 if (g < 3) AT_VLD(vn, g + 1);
;                 AT_SB;
;                 if ((g & 1) == 0) { lacc[0] = MFMA16(ones, pf[g >> 1][0], lacc[0]); lacc[1] = MFMA16(ones, pf[g >> 1][1], lacc[1]); }
; #pragma unroll
;                 for (int i = 0; i < 4; ++i) { const int dvb = 4 * (g & 1) + i; o[dvb][0] = MFMA16(vc[i], pf[g >> 1][0], o[dvb][0]); o[dvb][1] = MFMA16(vc[i], pf[g >> 1][1], o[dvb][1]); }
;                 AT_SB;
;                 if (g < 3) {
; #pragma unroll
;                     for (int i = 0; i < 4; ++i) vc[i] = vn[i]; }
;             }
.LBB0_631:
	v_exp_f32_e32 v160, v160
	v_exp_f32_e32 v161, v161
	v_exp_f32_e32 v162, v162
	v_exp_f32_e32 v163, v163
	v_exp_f32_e32 v164, v164
	v_exp_f32_e32 v165, v165
	v_exp_f32_e32 v166, v166
	v_exp_f32_e32 v167, v167
	v_exp_f32_e32 v156, v156
	v_exp_f32_e32 v157, v157
	v_exp_f32_e32 v158, v158
	v_exp_f32_e32 v159, v159
	v_exp_f32_e32 v206, v152
	v_exp_f32_e32 v207, v153
	v_exp_f32_e32 v224, v154
	v_exp_f32_e32 v225, v155
	v_cvt_pk_bf16_f32 v154, v160, v161
	v_cvt_pk_bf16_f32 v155, v162, v163
	v_exp_f32_e32 v148, v148
	v_exp_f32_e32 v149, v149
	v_exp_f32_e32 v150, v150
	v_exp_f32_e32 v151, v151
	v_exp_f32_e32 v144, v144
	v_exp_f32_e32 v145, v145
	v_exp_f32_e32 v146, v146
	v_exp_f32_e32 v147, v147
	v_exp_f32_e32 v140, v140
	v_exp_f32_e32 v141, v141
	v_exp_f32_e32 v142, v142
	v_exp_f32_e32 v143, v143
	v_exp_f32_e32 v160, v136
	v_exp_f32_e32 v161, v137
	v_exp_f32_e32 v162, v138
	v_exp_f32_e32 v163, v139
	v_cvt_pk_bf16_f32 v152, v164, v165
	v_cvt_pk_bf16_f32 v153, v166, v167
	v_cvt_pk_bf16_f32 v156, v156, v157
	v_cvt_pk_bf16_f32 v157, v158, v159
	v_cvt_pk_bf16_f32 v158, v206, v207
	v_cvt_pk_bf16_f32 v159, v224, v225
	v_cvt_pk_bf16_f32 v136, v148, v149
	v_cvt_pk_bf16_f32 v137, v150, v151
	v_cvt_pk_bf16_f32 v138, v144, v145
	v_cvt_pk_bf16_f32 v139, v146, v147
	v_cvt_pk_bf16_f32 v140, v140, v141
	v_cvt_pk_bf16_f32 v141, v142, v143
	v_cvt_pk_bf16_f32 v142, v160, v161
	v_cvt_pk_bf16_f32 v143, v162, v163
	v_add_u32_e32 v206, 0xa000, v223
	v_add_u32_e32 v207, 0xa800, v223
	v_add_u32_e32 v228, 0xb000, v223
	v_add_u32_e32 v223, 0xb800, v223
	ds_read_b64 v[144:145], v206 offset:1024
	ds_read_b64 v[146:147], v206 offset:1056
	ds_read_b64 v[148:149], v207 offset:1280
	ds_read_b64 v[150:151], v207 offset:1312
	ds_read_b64 v[160:161], v228 offset:1536
	ds_read_b64 v[162:163], v228 offset:1568
	ds_read_b64 v[164:165], v223 offset:1792
	ds_read_b64 v[166:167], v223 offset:1824
	s_mov_b32 s54, s52
	s_mov_b32 s55, s52
	s_mov_b32 s53, s52
	v_mov_b64_e32 v[226:227], s[54:55]
	v_mov_b64_e32 v[224:225], s[52:53]
	s_waitcnt lgkmcnt(0)
	v_mfma_f32_16x16x32_bf16 v[116:119], v[120:123], v[152:155], v[116:119]
	v_mfma_f32_16x16x32_bf16 v[112:115], v[224:227], v[152:155], v[112:115]
	v_mfma_f32_16x16x32_bf16 v[76:79], v[224:227], v[136:139], v[76:79]
	v_mfma_f32_16x16x32_bf16 v[84:87], v[120:123], v[136:139], v[84:87]
	v_mfma_f32_16x16x32_bf16 v[108:111], v[124:127], v[152:155], v[108:111]
	v_mfma_f32_16x16x32_bf16 v[80:83], v[124:127], v[136:139], v[80:83]
	v_mfma_f32_16x16x32_bf16 v[104:107], v[128:131], v[152:155], v[104:107]
	v_mfma_f32_16x16x32_bf16 v[68:71], v[128:131], v[136:139], v[68:71]
	v_mfma_f32_16x16x32_bf16 v[100:103], v[132:135], v[152:155], v[100:103]
	v_mfma_f32_16x16x32_bf16 v[64:67], v[132:135], v[136:139], v[64:67]
	ds_read_b64 v[120:121], v222 offset:64
	ds_read_b64 v[122:123], v222 offset:96
	ds_read_b64 v[124:125], v221 offset:320
	ds_read_b64 v[126:127], v221 offset:352
	ds_read_b64 v[128:129], v220 offset:576
	ds_read_b64 v[130:131], v220 offset:608
	ds_read_b64 v[132:133], v172 offset:832
	ds_read_b64 v[134:135], v172 offset:864
	v_mfma_f32_16x16x32_bf16 v[96:99], v[144:147], v[152:155], v[96:99]
	v_mfma_f32_16x16x32_bf16 v[60:63], v[144:147], v[136:139], v[60:63]
	v_mfma_f32_16x16x32_bf16 v[92:95], v[148:151], v[152:155], v[92:95]
	v_mfma_f32_16x16x32_bf16 v[56:59], v[148:151], v[136:139], v[56:59]
	v_mfma_f32_16x16x32_bf16 v[88:91], v[160:163], v[152:155], v[88:91]
	v_mfma_f32_16x16x32_bf16 v[52:55], v[160:163], v[136:139], v[52:55]
	v_mfma_f32_16x16x32_bf16 v[72:75], v[164:167], v[152:155], v[72:75]
	v_mfma_f32_16x16x32_bf16 v[48:51], v[164:167], v[136:139], v[48:51]
	ds_read_b64 v[136:137], v206 offset:1088
	ds_read_b64 v[138:139], v206 offset:1120
	ds_read_b64 v[144:145], v207 offset:1344
	ds_read_b64 v[146:147], v207 offset:1376
	ds_read_b64 v[148:149], v228 offset:1600
	ds_read_b64 v[150:151], v228 offset:1632
	ds_read_b64 v[152:153], v223 offset:1856
	ds_read_b64 v[154:155], v223 offset:1888
	v_mfma_f32_16x16x32_bf16 v[112:115], v[224:227], v[156:159], v[112:115]
	v_mfma_f32_16x16x32_bf16 v[76:79], v[224:227], v[140:143], v[76:79]
	s_waitcnt lgkmcnt(0)
	v_mfma_f32_16x16x32_bf16 v[116:119], v[120:123], v[156:159], v[116:119]
	v_mfma_f32_16x16x32_bf16 v[84:87], v[120:123], v[140:143], v[84:87]
	v_mfma_f32_16x16x32_bf16 v[108:111], v[124:127], v[156:159], v[108:111]
	v_mfma_f32_16x16x32_bf16 v[80:83], v[124:127], v[140:143], v[80:83]
	v_mfma_f32_16x16x32_bf16 v[104:107], v[128:131], v[156:159], v[104:107]
	v_mfma_f32_16x16x32_bf16 v[68:71], v[128:131], v[140:143], v[68:71]
	v_mfma_f32_16x16x32_bf16 v[100:103], v[132:135], v[156:159], v[100:103]
	v_mfma_f32_16x16x32_bf16 v[64:67], v[132:135], v[140:143], v[64:67]
	v_mfma_f32_16x16x32_bf16 v[96:99], v[136:139], v[156:159], v[96:99]
	v_mfma_f32_16x16x32_bf16 v[60:63], v[136:139], v[140:143], v[60:63]
	v_mfma_f32_16x16x32_bf16 v[92:95], v[144:147], v[156:159], v[92:95]
	v_mfma_f32_16x16x32_bf16 v[56:59], v[144:147], v[140:143], v[56:59]
	v_mfma_f32_16x16x32_bf16 v[88:91], v[148:151], v[156:159], v[88:91]
	v_mfma_f32_16x16x32_bf16 v[52:55], v[148:151], v[140:143], v[52:55]
	v_mfma_f32_16x16x32_bf16 v[72:75], v[152:155], v[156:159], v[72:75]
	v_mfma_f32_16x16x32_bf16 v[48:51], v[152:155], v[140:143], v[48:51]

; #define MFMA16(a, b, c) __builtin_amdgcn_mfma_f32_16x16x32_bf16((a), (b), (c), 0, 0, 0)
; #define AT_SB __builtin_amdgcn_sched_barrier(0)
; #define AT_KLD(dst, ks_) do { _Pragma("unroll") for (int kvb = 0; kvb < 4; ++kvb) dst[kvb] = *(const LAS bf16x8*)(Kl + kxo[(ks_) & 3] + ((ks_) >> 2) * 256 + kvb * (16 * 512)); } while (0)
; #define AT_VLD(dst, g_) do { _Pragma("unroll") for (int i_ = 0; i_ < 4; ++i_) { const LAS unsigned char* vp = Vl + (16 * (4 * ((g_) & 1) + i_) + fr) * 144 + (32 * ((g_) >> 1) + 4 * fq) * 2; \
;             const u32x2 lo = *(const LAS u32x2*)vp, hi = *(const LAS u32x2*)(vp + 32); u32x4 w; w.x = lo.x; w.y = lo.y; w.z = hi.x; w.w = hi.y; dst[i_] = __builtin_bit_cast(bf16x8, w); } } while (0)
; __device__ __forceinline__ void attn_unit(const Params& P, LAS unsigned char* lds, int bh, int qb) {
;     ...
;         if (k0 <= q0) {
;     ...
;             bf16x8 kc[4], kn[4];
;             AT_KLD(kc, 0);
;             f32x4 s[4][2];
; #pragma unroll
;             for (int kvb = 0; kvb < 4; ++kvb) { s[kvb][0] = (f32x4){-mrow[0], -mrow[0], -mrow[0], -mrow[0]}; s[kvb][1] = (f32x4){-mrow[1], -mrow[1], -mrow[1], -mrow[1]}; }
; #pragma unroll
;             for (int ks = 0; ks < 6; ++ks) {
;                 if (ks < 5) AT_KLD(kn, ks + 1);
;                 AT_SB;
; #pragma unroll
;                 for (int kvb = 0; kvb < 4; ++kvb) { s[kvb][0] = MFMA16(kc[kvb], qf[ks][0], s[kvb][0]); s[kvb][1] = MFMA16(kc[kvb], qf[ks][1], s[kvb][1]); }
;                 AT_SB;
;                 if (ks < 5) {
; #pragma unroll
;                     for (int kvb = 0; kvb < 4; ++kvb) kc[kvb] = kn[kvb]; }
;             }
;             bf16x8 vc[4], vn[4];
;             AT_VLD(vc, 0);
.LBB0_642:
	s_cmp_gt_i32 s85, s81
	s_cbranch_scc1 .LBB0_632
	s_mul_i32 s0, s0, 0xc800
	s_add_i32 s0, s0, 0
	v_add3_u32 v172, s0, v212, v211
	v_add3_u32 v206, s0, v213, v211
	ds_read_b128 v[120:123], v172
	ds_read_b128 v[124:127], v172 offset:8192
	ds_read_b128 v[128:131], v172 offset:16384
	ds_read_b128 v[132:135], v172 offset:24576
	ds_read_b128 v[140:143], v206
	ds_read_b128 v[144:147], v206 offset:8192
	ds_read_b128 v[148:151], v206 offset:16384
	ds_read_b128 v[152:155], v206 offset:24576
	v_xor_b32_e32 v136, 0x80000000, v205
	v_xor_b32_e32 v156, 0x80000000, v204
	v_mov_b32_e32 v137, v136
	v_mov_b32_e32 v138, v136
	v_mov_b32_e32 v139, v136
	v_mov_b32_e32 v157, v156
	v_mov_b32_e32 v158, v156
	v_mov_b32_e32 v159, v156
	s_waitcnt lgkmcnt(0)
	v_mfma_f32_16x16x32_bf16 v[160:163], v[120:123], v[0:3], v[136:139]
	v_mfma_f32_16x16x32_bf16 v[120:123], v[120:123], v[24:27], v[156:159]
	v_mfma_f32_16x16x32_bf16 v[164:167], v[124:127], v[0:3], v[136:139]
	v_mfma_f32_16x16x32_bf16 v[124:127], v[124:127], v[24:27], v[156:159]
	v_mfma_f32_16x16x32_bf16 v[220:223], v[128:131], v[0:3], v[136:139]
	v_mfma_f32_16x16x32_bf16 v[128:131], v[128:131], v[24:27], v[156:159]
	v_mfma_f32_16x16x32_bf16 v[136:139], v[132:135], v[0:3], v[136:139]
	v_mfma_f32_16x16x32_bf16 v[132:135], v[132:135], v[24:27], v[156:159]
	v_add3_u32 v207, s0, v214, v211
	s_nop 1
	ds_read_b128 v[156:159], v207
	ds_read_b128 v[224:227], v207 offset:8192
	ds_read_b128 v[228:231], v207 offset:16384
	ds_read_b128 v[232:235], v207 offset:24576
	v_mfma_f32_16x16x32_bf16 v[160:163], v[140:143], v[4:7], v[160:163]
	v_mfma_f32_16x16x32_bf16 v[120:123], v[140:143], v[28:31], v[120:123]
	v_mfma_f32_16x16x32_bf16 v[140:143], v[144:147], v[4:7], v[164:167]
	v_mfma_f32_16x16x32_bf16 v[124:127], v[144:147], v[28:31], v[124:127]
	v_mfma_f32_16x16x32_bf16 v[144:147], v[148:151], v[4:7], v[220:223]
	v_mfma_f32_16x16x32_bf16 v[128:131], v[148:151], v[28:31], v[128:131]
	v_mfma_f32_16x16x32_bf16 v[136:139], v[152:155], v[4:7], v[136:139]
	v_mfma_f32_16x16x32_bf16 v[132:135], v[152:155], v[28:31], v[132:135]
	v_add3_u32 v207, s0, v216, v211
	ds_read_b128 v[148:151], v207
	ds_read_b128 v[152:155], v207 offset:8192
	ds_read_b128 v[164:167], v207 offset:16384
	ds_read_b128 v[220:223], v207 offset:24576
	s_waitcnt lgkmcnt(0)
	v_mfma_f32_16x16x32_bf16 v[160:163], v[156:159], v[8:11], v[160:163]
	v_mfma_f32_16x16x32_bf16 v[120:123], v[156:159], v[32:35], v[120:123]
	v_mfma_f32_16x16x32_bf16 v[140:143], v[224:227], v[8:11], v[140:143]
	v_mfma_f32_16x16x32_bf16 v[124:127], v[224:227], v[32:35], v[124:127]
	v_mfma_f32_16x16x32_bf16 v[144:147], v[228:231], v[8:11], v[144:147]
	v_mfma_f32_16x16x32_bf16 v[128:131], v[228:231], v[32:35], v[128:131]
	v_mfma_f32_16x16x32_bf16 v[136:139], v[232:235], v[8:11], v[136:139]
	v_mfma_f32_16x16x32_bf16 v[132:135], v[232:235], v[32:35], v[132:135]
	ds_read_b128 v[156:159], v172 offset:256
	ds_read_b128 v[224:227], v172 offset:8448
	ds_read_b128 v[228:231], v172 offset:16640
	ds_read_b128 v[232:235], v172 offset:24832
	v_mfma_f32_16x16x32_bf16 v[160:163], v[148:151], v[12:15], v[160:163]
	v_mfma_f32_16x16x32_bf16 v[120:123], v[148:151], v[36:39], v[120:123]
	v_mfma_f32_16x16x32_bf16 v[140:143], v[152:155], v[12:15], v[140:143]
	v_mfma_f32_16x16x32_bf16 v[124:127], v[152:155], v[36:39], v[124:127]
	v_mfma_f32_16x16x32_bf16 v[144:147], v[164:167], v[12:15], v[144:147]
	v_mfma_f32_16x16x32_bf16 v[128:131], v[164:167], v[36:39], v[128:131]
	v_mfma_f32_16x16x32_bf16 v[136:139], v[220:223], v[12:15], v[136:139]
	v_mfma_f32_16x16x32_bf16 v[132:135], v[220:223], v[36:39], v[132:135]
	ds_read_b128 v[148:151], v206 offset:256
	ds_read_b128 v[152:155], v206 offset:8448
	ds_read_b128 v[220:223], v206 offset:16640
	ds_read_b128 v[236:239], v206 offset:24832
	s_waitcnt lgkmcnt(0)
	v_mfma_f32_16x16x32_bf16 v[160:163], v[156:159], v[16:19], v[160:163]
	v_mfma_f32_16x16x32_bf16 v[120:123], v[156:159], v[40:43], v[120:123]
	v_mfma_f32_16x16x32_bf16 v[140:143], v[224:227], v[16:19], v[140:143]
	v_mfma_f32_16x16x32_bf16 v[124:127], v[224:227], v[40:43], v[124:127]
	v_mfma_f32_16x16x32_bf16 v[156:159], v[228:231], v[16:19], v[144:147]
	v_mfma_f32_16x16x32_bf16 v[128:131], v[228:231], v[40:43], v[128:131]
	v_mfma_f32_16x16x32_bf16 v[136:139], v[232:235], v[16:19], v[136:139]
	v_mfma_f32_16x16x32_bf16 v[132:135], v[232:235], v[40:43], v[132:135]
	v_mfma_f32_16x16x32_bf16 v[164:167], v[148:151], v[20:23], v[160:163]
	v_mfma_f32_16x16x32_bf16 v[148:151], v[148:151], v[44:47], v[120:123]
	v_mfma_f32_16x16x32_bf16 v[160:163], v[152:155], v[20:23], v[140:143]
	v_mfma_f32_16x16x32_bf16 v[144:147], v[152:155], v[44:47], v[124:127]
	v_mfma_f32_16x16x32_bf16 v[156:159], v[220:223], v[20:23], v[156:159]
	v_mfma_f32_16x16x32_bf16 v[140:143], v[220:223], v[44:47], v[128:131]
	v_mfma_f32_16x16x32_bf16 v[152:155], v[236:239], v[20:23], v[136:139]
	v_mfma_f32_16x16x32_bf16 v[136:139], v[236:239], v[44:47], v[132:135]
	v_add_u32_e32 v120, s0, v210
	v_add_u32_e32 v223, v120, v218
	v_add_u32_e32 v222, 0x8000, v223
	v_add_u32_e32 v221, 0x8800, v223
	v_add_u32_e32 v220, 0x9000, v223
	v_add_u32_e32 v172, 0x9800, v223
	ds_read_b64 v[120:121], v222
	ds_read_b64 v[122:123], v222 offset:32
	ds_read_b64 v[124:125], v221 offset:256
	ds_read_b64 v[126:127], v221 offset:288
	ds_read_b64 v[128:129], v220 offset:512
	ds_read_b64 v[130:131], v220 offset:544
	ds_read_b64 v[132:133], v172 offset:768
	ds_read_b64 v[134:135], v172 offset:800
	s_add_i32 s0, s85, 63
	s_cmp_le_i32 s0, s81
	s_cbranch_scc1 .LBB0_645
; __device__ __forceinline__ void attn_unit(const Params& P, LAS unsigned char* lds, int bh, int qb) {
;     ...
;             if (k0 + 63 > q0) {
; #pragma unroll
;                 for (int kvb = 0; kvb < 4; ++kvb)
; #pragma unroll
;                     for (int qk = 0; qk < 2; ++qk)
; #pragma unroll
;                         for (int e = 0; e < 4; ++e) { const int kv = k0 + 16 * kvb + 4 * fq + e, q = q0 + 16 * qk + fr; if (kv > q) s[kvb][qk][e] = -INFINITY; }
;             }
	v_add_u32_e32 v207, s85, v215
	v_cmp_gt_i32_e32 vcc, v207, v217
	v_mov_b32_e32 v206, s79
	v_cmp_lt_i32_e64 s[0:1], v207, v217
	v_cndmask_b32_e32 v206, v164, v206, vcc
	v_add_u32_e32 v224, 2, v207
	v_cndmask_b32_e64 v164, v206, v164, s[0:1]
	v_cndmask_b32_e64 v165, v209, v165, s[0:1]
	v_cmp_le_i32_e64 s[0:1], v224, v217
	v_add_u32_e32 v225, 3, v207
	v_mov_b32_e32 v206, s79
	v_cndmask_b32_e64 v166, v209, v166, s[0:1]
	v_cmp_le_i32_e64 s[0:1], v225, v217
	v_add_u32_e32 v226, 19, v207
	v_add_u32_e32 v227, 35, v207
	v_cndmask_b32_e64 v167, v209, v167, s[0:1]
	v_cmp_gt_i32_e64 s[0:1], v207, v219
	s_nop 1
	v_cndmask_b32_e64 v206, v148, v206, s[0:1]
	v_cmp_lt_i32_e64 s[0:1], v207, v219
	s_nop 1
	v_cndmask_b32_e64 v148, v206, v148, s[0:1]
	v_cndmask_b32_e64 v149, v209, v149, s[0:1]
	v_cmp_le_i32_e64 s[0:1], v224, v219
	v_add_u32_e32 v206, 16, v207
	v_add_u32_e32 v224, 17, v207
	v_cndmask_b32_e64 v150, v209, v150, s[0:1]
	v_cmp_le_i32_e64 s[0:1], v225, v219
	v_add_u32_e32 v225, 18, v207
	s_nop 0
	v_cndmask_b32_e64 v151, v209, v151, s[0:1]
	v_cmp_gt_i32_e64 s[0:1], v206, v217
	v_mov_b32_e32 v206, s79
	v_cndmask_b32_e32 v144, v144, v206, vcc
	v_cmp_le_i32_e32 vcc, v224, v219
	v_cndmask_b32_e64 v160, v160, v206, s[0:1]
	v_cmp_le_i32_e64 s[0:1], v224, v217
	v_cndmask_b32_e32 v145, v209, v145, vcc
	v_cmp_le_i32_e32 vcc, v225, v219
	v_add_u32_e32 v224, 32, v207
	v_cndmask_b32_e64 v161, v209, v161, s[0:1]
	v_cndmask_b32_e32 v146, v209, v146, vcc
	v_cmp_le_i32_e32 vcc, v226, v219
	v_cmp_le_i32_e64 s[0:1], v225, v217
	v_add_u32_e32 v225, 33, v207
	v_cndmask_b32_e32 v147, v209, v147, vcc
	v_cmp_gt_i32_e32 vcc, v224, v217
	v_cndmask_b32_e64 v162, v209, v162, s[0:1]
	v_cmp_le_i32_e64 s[0:1], v226, v217
	v_cndmask_b32_e32 v156, v156, v206, vcc
	v_cmp_le_i32_e32 vcc, v225, v217
	v_add_u32_e32 v226, 34, v207
	v_cndmask_b32_e64 v163, v209, v163, s[0:1]
	v_cndmask_b32_e32 v157, v209, v157, vcc
	v_cmp_le_i32_e32 vcc, v226, v217
	s_nop 1
	v_cndmask_b32_e32 v158, v209, v158, vcc
	v_cmp_le_i32_e32 vcc, v227, v217
	s_nop 1
	v_cndmask_b32_e32 v159, v209, v159, vcc
	v_cmp_gt_i32_e32 vcc, v224, v219
	v_add_u32_e32 v224, 48, v207
	s_nop 0
	v_cndmask_b32_e32 v140, v140, v206, vcc
	v_cmp_le_i32_e32 vcc, v225, v219
	v_add_u32_e32 v225, 49, v207
	s_nop 0
	v_cndmask_b32_e32 v141, v209, v141, vcc
	v_cmp_le_i32_e32 vcc, v226, v219
	v_add_u32_e32 v226, 50, v207
	v_add_u32_e32 v207, 51, v207
	v_cndmask_b32_e32 v142, v209, v142, vcc
	v_cmp_le_i32_e32 vcc, v227, v219
	s_nop 1
	v_cndmask_b32_e32 v143, v209, v143, vcc
	v_cmp_gt_i32_e32 vcc, v224, v217
	s_nop 1
	v_cndmask_b32_e32 v152, v152, v206, vcc
	v_cmp_le_i32_e32 vcc, v225, v217
	s_nop 1
	v_cndmask_b32_e32 v153, v209, v153, vcc
	v_cmp_le_i32_e32 vcc, v226, v217
	s_nop 1
	v_cndmask_b32_e32 v154, v209, v154, vcc
	v_cmp_le_i32_e32 vcc, v207, v217
	s_nop 1
	v_cndmask_b32_e32 v155, v209, v155, vcc
	v_cmp_gt_i32_e32 vcc, v224, v219
	s_nop 1
	v_cndmask_b32_e32 v136, v136, v206, vcc
	v_cmp_le_i32_e32 vcc, v225, v219
	s_nop 1
	v_cndmask_b32_e32 v137, v209, v137, vcc
	v_cmp_le_i32_e32 vcc, v226, v219
	s_nop 1
	v_cndmask_b32_e32 v138, v209, v138, vcc
	v_cmp_le_i32_e32 vcc, v207, v219
	s_nop 1
	v_cndmask_b32_e32 v139, v209, v139, vcc
